# trailing wave half gets the epilogue priority raise instead of the leading half (direction check of the epilogue-priority lever)
# baseline (speedup 1.0000x reference)
.LBB0_384:
	ds_read_b128 v[134:137], v199
	ds_read_b128 v[138:141], v200
	ds_read_b128 v[142:145], v201
	ds_read_b128 v[146:149], v202
	ds_read_b128 v[150:153], v203
	ds_read_b128 v[174:177], v204
	ds_read_b128 v[178:181], v205
	ds_read_b128 v[182:185], v206
	s_add_u32 s24, s4, vcc_lo
	s_addc_u32 s25, s5, vcc_hi
	s_add_u32 s24, s24, 0x100
	s_addc_u32 s25, s25, 0
	s_add_u32 s82, s39, vcc_lo
	s_addc_u32 s83, s67, vcc_hi
	s_cmpk_eq_i32 vcc_lo, 0x700
	s_cselect_b32 s87, s29, s83
	s_cselect_b32 s86, s38, s82
	s_cselect_b32 s83, s34, s25
	s_cselect_b32 s82, s35, s24
	v_lshl_add_u64 v[154:155], v[132:133], 0, vcc
	v_lshl_add_u64 v[250:251], v[154:155], 0, s[48:49]
	s_add_i32 m0, s79, 0x8000
	s_mov_b64 s[24:25], 0x20080
	ds_read_b128 v[218:221], v207
	ds_read_b128 v[222:225], v207 offset:2048
	ds_read_b128 v[226:229], v208
	ds_read_b128 v[230:233], v208 offset:2048
	ds_read_b128 v[234:237], v207 offset:4096
	ds_read_b128 v[238:241], v207 offset:6144
	ds_read_b128 v[242:245], v208 offset:4096
	ds_read_b128 v[246:249], v208 offset:6144
	global_load_lds_dwordx4 v[250:251], off
	v_lshl_add_u64 v[250:251], v[154:155], 0, s[24:25]
	s_add_i32 m0, s79, 0xa000
	s_mov_b64 s[24:25], 0x60080
	global_load_lds_dwordx4 v[250:251], off
	v_lshl_add_u64 v[250:251], v[154:155], 0, s[50:51]
	s_add_i32 m0, s79, 0xc000
	v_lshl_add_u64 v[154:155], v[154:155], 0, s[24:25]
	global_load_lds_dwordx4 v[250:251], off
	s_add_i32 m0, s79, 0xe000
	s_nop 0
	global_load_lds_dwordx4 v[154:155], off
	s_waitcnt vmcnt(8)
	s_waitcnt lgkmcnt(0)
	s_barrier
	v_mfma_f32_16x16x32_bf16 v[128:131], v[134:137], v[218:221], v[128:131]
	v_mfma_f32_16x16x32_bf16 v[128:131], v[138:141], v[226:229], v[128:131]
	v_mfma_f32_16x16x32_bf16 v[112:115], v[138:141], v[230:233], v[112:115]
	v_mfma_f32_16x16x32_bf16 v[112:115], v[134:137], v[222:225], v[112:115]
	v_mfma_f32_16x16x32_bf16 v[96:99], v[134:137], v[234:237], v[96:99]
	v_mfma_f32_16x16x32_bf16 v[96:99], v[138:141], v[242:245], v[96:99]
	v_mfma_f32_16x16x32_bf16 v[80:83], v[138:141], v[246:249], v[80:83]
	v_mfma_f32_16x16x32_bf16 v[80:83], v[134:137], v[238:241], v[80:83]
	v_mfma_f32_16x16x32_bf16 v[76:79], v[142:145], v[238:241], v[76:79]
	v_mfma_f32_16x16x32_bf16 v[76:79], v[146:149], v[246:249], v[76:79]
	v_mfma_f32_16x16x32_bf16 v[92:95], v[146:149], v[242:245], v[92:95]
	v_mfma_f32_16x16x32_bf16 v[92:95], v[142:145], v[234:237], v[92:95]
	v_mfma_f32_16x16x32_bf16 v[108:111], v[142:145], v[222:225], v[108:111]
	v_mfma_f32_16x16x32_bf16 v[108:111], v[146:149], v[230:233], v[108:111]
	v_mfma_f32_16x16x32_bf16 v[124:127], v[146:149], v[226:229], v[124:127]
	v_mfma_f32_16x16x32_bf16 v[124:127], v[142:145], v[218:221], v[124:127]
	v_mfma_f32_16x16x32_bf16 v[120:123], v[150:153], v[218:221], v[120:123]
	v_mfma_f32_16x16x32_bf16 v[120:123], v[174:177], v[226:229], v[120:123]
	v_mfma_f32_16x16x32_bf16 v[104:107], v[174:177], v[230:233], v[104:107]
	v_mfma_f32_16x16x32_bf16 v[104:107], v[150:153], v[222:225], v[104:107]
	v_mfma_f32_16x16x32_bf16 v[88:91], v[150:153], v[234:237], v[88:91]
	v_mfma_f32_16x16x32_bf16 v[88:91], v[174:177], v[242:245], v[88:91]
	v_mfma_f32_16x16x32_bf16 v[72:75], v[174:177], v[246:249], v[72:75]
	v_mfma_f32_16x16x32_bf16 v[72:75], v[150:153], v[238:241], v[72:75]
	v_mfma_f32_16x16x32_bf16 v[68:71], v[178:181], v[238:241], v[68:71]
	v_mfma_f32_16x16x32_bf16 v[68:71], v[182:185], v[246:249], v[68:71]
	v_mfma_f32_16x16x32_bf16 v[84:87], v[182:185], v[242:245], v[84:87]
	v_mfma_f32_16x16x32_bf16 v[84:87], v[178:181], v[234:237], v[84:87]
	v_mfma_f32_16x16x32_bf16 v[100:103], v[178:181], v[222:225], v[100:103]
	v_mfma_f32_16x16x32_bf16 v[100:103], v[182:185], v[230:233], v[100:103]
	v_mfma_f32_16x16x32_bf16 v[116:119], v[182:185], v[226:229], v[116:119]
	v_mfma_f32_16x16x32_bf16 v[116:119], v[178:181], v[218:221], v[116:119]
	s_barrier
	s_add_i32 s24, s1, s77
	v_lshl_add_u64 v[154:155], s[86:87], 0, v[158:159]
	s_mov_b32 m0, s24
	ds_read_b128 v[218:221], v207 offset:16384
	ds_read_b128 v[222:225], v207 offset:18432
	ds_read_b128 v[226:229], v208 offset:16384
	ds_read_b128 v[230:233], v208 offset:18432
	ds_read_b128 v[234:237], v207 offset:20480
	ds_read_b128 v[238:241], v207 offset:22528
	ds_read_b128 v[242:245], v208 offset:20480
	ds_read_b128 v[246:249], v208 offset:22528
	global_load_lds_dwordx4 v[154:155], off
	v_lshl_add_u64 v[250:251], v[154:155], 0, s[14:15]
	s_add_i32 m0, s24, 0x2000
	s_add_i32 s24, s12, s77
	global_load_lds_dwordx4 v[250:251], off
	v_lshl_add_u64 v[250:251], v[154:155], 0, s[16:17]
	s_mov_b32 m0, s24
	s_nop 0
	global_load_lds_dwordx4 v[250:251], off
	v_lshl_add_u64 v[250:251], v[154:155], 0, s[18:19]
	s_add_i32 m0, s24, 0x2000
	s_nop 0
	global_load_lds_dwordx4 v[250:251], off
	s_waitcnt vmcnt(4)
	s_waitcnt lgkmcnt(0)
	s_barrier
	v_mfma_f32_16x16x32_bf16 v[64:67], v[134:137], v[218:221], v[64:67]
	v_mfma_f32_16x16x32_bf16 v[64:67], v[138:141], v[226:229], v[64:67]
	v_mfma_f32_16x16x32_bf16 v[48:51], v[138:141], v[230:233], v[48:51]
	v_mfma_f32_16x16x32_bf16 v[48:51], v[134:137], v[222:225], v[48:51]
	v_mfma_f32_16x16x32_bf16 v[32:35], v[134:137], v[234:237], v[32:35]
	v_mfma_f32_16x16x32_bf16 v[32:35], v[138:141], v[242:245], v[32:35]
	v_mfma_f32_16x16x32_bf16 v[16:19], v[138:141], v[246:249], v[16:19]
	v_mfma_f32_16x16x32_bf16 v[16:19], v[134:137], v[238:241], v[16:19]
	v_mfma_f32_16x16x32_bf16 v[12:15], v[142:145], v[238:241], v[12:15]
	v_mfma_f32_16x16x32_bf16 v[12:15], v[146:149], v[246:249], v[12:15]
	v_mfma_f32_16x16x32_bf16 v[28:31], v[146:149], v[242:245], v[28:31]
	v_mfma_f32_16x16x32_bf16 v[28:31], v[142:145], v[234:237], v[28:31]
	v_mfma_f32_16x16x32_bf16 v[44:47], v[142:145], v[222:225], v[44:47]
	v_mfma_f32_16x16x32_bf16 v[44:47], v[146:149], v[230:233], v[44:47]
	v_mfma_f32_16x16x32_bf16 v[60:63], v[146:149], v[226:229], v[60:63]
	v_mfma_f32_16x16x32_bf16 v[60:63], v[142:145], v[218:221], v[60:63]
	v_mfma_f32_16x16x32_bf16 v[56:59], v[150:153], v[218:221], v[56:59]
	v_mfma_f32_16x16x32_bf16 v[56:59], v[174:177], v[226:229], v[56:59]
	v_mfma_f32_16x16x32_bf16 v[40:43], v[174:177], v[230:233], v[40:43]
	v_mfma_f32_16x16x32_bf16 v[40:43], v[150:153], v[222:225], v[40:43]
	v_mfma_f32_16x16x32_bf16 v[24:27], v[150:153], v[234:237], v[24:27]
	v_mfma_f32_16x16x32_bf16 v[24:27], v[174:177], v[242:245], v[24:27]
	v_mfma_f32_16x16x32_bf16 v[8:11], v[174:177], v[246:249], v[8:11]
	v_mfma_f32_16x16x32_bf16 v[8:11], v[150:153], v[238:241], v[8:11]
	v_mfma_f32_16x16x32_bf16 v[4:7], v[178:181], v[238:241], v[4:7]
	v_mfma_f32_16x16x32_bf16 v[4:7], v[182:185], v[246:249], v[4:7]
	v_mfma_f32_16x16x32_bf16 v[20:23], v[182:185], v[242:245], v[20:23]
	v_mfma_f32_16x16x32_bf16 v[20:23], v[178:181], v[234:237], v[20:23]
	v_mfma_f32_16x16x32_bf16 v[36:39], v[178:181], v[222:225], v[36:39]
	v_mfma_f32_16x16x32_bf16 v[36:39], v[182:185], v[230:233], v[36:39]
	v_mfma_f32_16x16x32_bf16 v[52:55], v[182:185], v[226:229], v[52:55]
	v_mfma_f32_16x16x32_bf16 v[52:55], v[178:181], v[218:221], v[52:55]
	s_barrier
	ds_read_b128 v[134:137], v213
	ds_read_b128 v[138:141], v214
	ds_read_b128 v[142:145], v209
	ds_read_b128 v[146:149], v210
	ds_read_b128 v[150:153], v215
	ds_read_b128 v[174:177], v216
	ds_read_b128 v[178:181], v211
	ds_read_b128 v[182:185], v212
	s_mov_b32 m0, s79
	v_lshl_add_u64 v[250:251], s[82:83], 0, v[0:1]
	ds_read_b128 v[218:221], v207 offset:32768
	ds_read_b128 v[222:225], v207 offset:34816
	ds_read_b128 v[226:229], v208 offset:32768
	ds_read_b128 v[230:233], v208 offset:34816
	ds_read_b128 v[234:237], v207 offset:36864
	ds_read_b128 v[238:241], v207 offset:38912
	ds_read_b128 v[242:245], v208 offset:36864
	ds_read_b128 v[246:249], v208 offset:38912
	global_load_lds_dwordx4 v[250:251], off
	v_lshl_add_u64 v[252:253], v[250:251], 0, s[20:21]
	s_mov_b32 m0, s81
	s_nop 0
	global_load_lds_dwordx4 v[252:253], off
	v_lshl_add_u64 v[252:253], v[250:251], 0, s[14:15]
	s_mov_b32 m0, s97
	v_lshl_add_u64 v[250:251], v[250:251], 0, s[22:23]
	global_load_lds_dwordx4 v[252:253], off
	s_mov_b32 m0, s64
	s_nop 0
	global_load_lds_dwordx4 v[250:251], off
	s_waitcnt vmcnt(8)
	s_waitcnt lgkmcnt(0)
	s_barrier
	v_mfma_f32_16x16x32_bf16 v[128:131], v[134:137], v[218:221], v[128:131]
	v_mfma_f32_16x16x32_bf16 v[128:131], v[138:141], v[226:229], v[128:131]
	v_mfma_f32_16x16x32_bf16 v[112:115], v[138:141], v[230:233], v[112:115]
	v_mfma_f32_16x16x32_bf16 v[112:115], v[134:137], v[222:225], v[112:115]
	v_mfma_f32_16x16x32_bf16 v[96:99], v[134:137], v[234:237], v[96:99]
	v_mfma_f32_16x16x32_bf16 v[96:99], v[138:141], v[242:245], v[96:99]
	v_mfma_f32_16x16x32_bf16 v[80:83], v[138:141], v[246:249], v[80:83]
	v_mfma_f32_16x16x32_bf16 v[80:83], v[134:137], v[238:241], v[80:83]
	v_mfma_f32_16x16x32_bf16 v[76:79], v[142:145], v[238:241], v[76:79]
	v_mfma_f32_16x16x32_bf16 v[76:79], v[146:149], v[246:249], v[76:79]
	v_mfma_f32_16x16x32_bf16 v[92:95], v[146:149], v[242:245], v[92:95]
	v_mfma_f32_16x16x32_bf16 v[92:95], v[142:145], v[234:237], v[92:95]
	v_mfma_f32_16x16x32_bf16 v[108:111], v[142:145], v[222:225], v[108:111]
	v_mfma_f32_16x16x32_bf16 v[108:111], v[146:149], v[230:233], v[108:111]
	v_mfma_f32_16x16x32_bf16 v[124:127], v[146:149], v[226:229], v[124:127]
	v_mfma_f32_16x16x32_bf16 v[124:127], v[142:145], v[218:221], v[124:127]
	v_mfma_f32_16x16x32_bf16 v[120:123], v[150:153], v[218:221], v[120:123]
	v_mfma_f32_16x16x32_bf16 v[120:123], v[174:177], v[226:229], v[120:123]
	v_mfma_f32_16x16x32_bf16 v[104:107], v[174:177], v[230:233], v[104:107]
	v_mfma_f32_16x16x32_bf16 v[104:107], v[150:153], v[222:225], v[104:107]
	v_mfma_f32_16x16x32_bf16 v[88:91], v[150:153], v[234:237], v[88:91]
	v_mfma_f32_16x16x32_bf16 v[88:91], v[174:177], v[242:245], v[88:91]
	v_mfma_f32_16x16x32_bf16 v[72:75], v[174:177], v[246:249], v[72:75]
	v_mfma_f32_16x16x32_bf16 v[72:75], v[150:153], v[238:241], v[72:75]
	v_mfma_f32_16x16x32_bf16 v[68:71], v[178:181], v[238:241], v[68:71]
	v_mfma_f32_16x16x32_bf16 v[68:71], v[182:185], v[246:249], v[68:71]
	v_mfma_f32_16x16x32_bf16 v[84:87], v[182:185], v[242:245], v[84:87]
	v_mfma_f32_16x16x32_bf16 v[84:87], v[178:181], v[234:237], v[84:87]
	v_mfma_f32_16x16x32_bf16 v[100:103], v[178:181], v[222:225], v[100:103]
	v_mfma_f32_16x16x32_bf16 v[100:103], v[182:185], v[230:233], v[100:103]
	v_mfma_f32_16x16x32_bf16 v[116:119], v[182:185], v[226:229], v[116:119]
	v_mfma_f32_16x16x32_bf16 v[116:119], v[178:181], v[218:221], v[116:119]
	s_barrier
	s_add_i32 s24, s70, s77
	v_lshl_add_u64 v[250:251], v[154:155], 0, s[48:49]
	s_mov_b32 m0, s24
	ds_read_b128 v[218:221], v207 offset:49152
	ds_read_b128 v[222:225], v207 offset:51200
	ds_read_b128 v[226:229], v208 offset:49152
	ds_read_b128 v[230:233], v208 offset:51200
	ds_read_b128 v[234:237], v207 offset:53248
	ds_read_b128 v[238:241], v207 offset:55296
	ds_read_b128 v[242:245], v208 offset:53248
	ds_read_b128 v[246:249], v208 offset:55296
	global_load_lds_dwordx4 v[250:251], off
	v_lshl_add_u64 v[250:251], v[154:155], 0, s[50:51]
	s_add_i32 m0, s24, 0x2000
	s_add_i32 s24, s71, s77
	global_load_lds_dwordx4 v[250:251], off
	v_lshl_add_u64 v[250:251], v[154:155], 0, s[52:53]
	s_mov_b32 m0, s24
	v_lshl_add_u64 v[154:155], v[154:155], 0, s[54:55]
	global_load_lds_dwordx4 v[250:251], off
	s_add_i32 m0, s24, 0x2000
	s_nop 0
	global_load_lds_dwordx4 v[154:155], off
	s_waitcnt vmcnt(4)
	s_waitcnt lgkmcnt(0)
	s_barrier
	v_mfma_f32_16x16x32_bf16 v[64:67], v[134:137], v[218:221], v[64:67]
	v_mfma_f32_16x16x32_bf16 v[64:67], v[138:141], v[226:229], v[64:67]
	v_mfma_f32_16x16x32_bf16 v[48:51], v[138:141], v[230:233], v[48:51]
	v_mfma_f32_16x16x32_bf16 v[48:51], v[134:137], v[222:225], v[48:51]
	v_mfma_f32_16x16x32_bf16 v[32:35], v[134:137], v[234:237], v[32:35]
	v_mfma_f32_16x16x32_bf16 v[32:35], v[138:141], v[242:245], v[32:35]
	v_mfma_f32_16x16x32_bf16 v[16:19], v[138:141], v[246:249], v[16:19]
	v_mfma_f32_16x16x32_bf16 v[16:19], v[134:137], v[238:241], v[16:19]
	v_mfma_f32_16x16x32_bf16 v[12:15], v[142:145], v[238:241], v[12:15]
	v_mfma_f32_16x16x32_bf16 v[12:15], v[146:149], v[246:249], v[12:15]
	v_mfma_f32_16x16x32_bf16 v[28:31], v[146:149], v[242:245], v[28:31]
	v_mfma_f32_16x16x32_bf16 v[28:31], v[142:145], v[234:237], v[28:31]
	v_mfma_f32_16x16x32_bf16 v[44:47], v[142:145], v[222:225], v[44:47]
	v_mfma_f32_16x16x32_bf16 v[44:47], v[146:149], v[230:233], v[44:47]
	v_mfma_f32_16x16x32_bf16 v[60:63], v[146:149], v[226:229], v[60:63]
	v_mfma_f32_16x16x32_bf16 v[60:63], v[142:145], v[218:221], v[60:63]
	v_mfma_f32_16x16x32_bf16 v[56:59], v[150:153], v[218:221], v[56:59]
	v_mfma_f32_16x16x32_bf16 v[56:59], v[174:177], v[226:229], v[56:59]
	v_mfma_f32_16x16x32_bf16 v[40:43], v[174:177], v[230:233], v[40:43]
	v_mfma_f32_16x16x32_bf16 v[40:43], v[150:153], v[222:225], v[40:43]
	v_mfma_f32_16x16x32_bf16 v[24:27], v[150:153], v[234:237], v[24:27]
	v_mfma_f32_16x16x32_bf16 v[24:27], v[174:177], v[242:245], v[24:27]
	v_mfma_f32_16x16x32_bf16 v[8:11], v[174:177], v[246:249], v[8:11]
	v_mfma_f32_16x16x32_bf16 v[8:11], v[150:153], v[238:241], v[8:11]
	v_mfma_f32_16x16x32_bf16 v[4:7], v[178:181], v[238:241], v[4:7]
	v_mfma_f32_16x16x32_bf16 v[4:7], v[182:185], v[246:249], v[4:7]
	v_mfma_f32_16x16x32_bf16 v[20:23], v[182:185], v[242:245], v[20:23]
	v_mfma_f32_16x16x32_bf16 v[20:23], v[178:181], v[234:237], v[20:23]
	v_mfma_f32_16x16x32_bf16 v[36:39], v[178:181], v[222:225], v[36:39]
	v_mfma_f32_16x16x32_bf16 v[36:39], v[182:185], v[230:233], v[36:39]
	v_mfma_f32_16x16x32_bf16 v[52:55], v[182:185], v[226:229], v[52:55]
	v_mfma_f32_16x16x32_bf16 v[52:55], v[178:181], v[218:221], v[52:55]
	s_barrier
	s_add_i32 s94, s94, 2
	s_add_u32 vcc_lo, vcc_lo, 0x100
	s_addc_u32 vcc_hi, vcc_hi, 0
	s_cmp_gt_u32 s94, 13
	s_cbranch_scc0 .LBB0_384
	s_and_b64 vcc, exec, s[56:57]
	s_cbranch_vccz .Lp1_wr1_epi
	s_barrier
	s_branch .LBB0_387
.Lp1_wr1_epi:
	s_setprio 2

.LBB0_488:
	v_readlane_b32 s4, v254, 22
	v_readlane_b32 s5, v254, 23
	s_andn2_b64 vcc, exec, s[4:5]
	s_cbranch_vccnz .LBB0_379
	s_barrier
	s_setprio 0
	s_branch .LBB0_379

.LBB0_1135:
	ds_read_b128 v[168:171], v145
	ds_read_b128 v[174:177], v146
	ds_read_b128 v[178:181], v147
	ds_read_b128 v[182:185], v148
	ds_read_b128 v[194:197], v149
	ds_read_b128 v[198:201], v150
	ds_read_b128 v[202:205], v151
	ds_read_b128 v[206:209], v152
	s_add_u32 s70, s26, s68
	s_addc_u32 s71, s27, s69
	s_add_u32 s70, s70, 0x100
	s_addc_u32 s71, s71, 0
	s_add_u32 s84, s81, s68
	s_addc_u32 s85, s82, s69
	s_cmpk_eq_i32 s68, 0x700
	s_cselect_b32 s85, s59, s85
	s_cselect_b32 s84, s80, s84
	s_cselect_b32 s71, s57, s71
	s_cselect_b32 s70, s79, s70
	v_lshl_add_u64 v[140:141], v[138:139], 0, s[68:69]
	v_lshl_add_u64 v[242:243], v[140:141], 0, s[22:23]
	s_add_i32 m0, s34, 0x8000
	s_mov_b64 s[86:87], 0x20080
	ds_read_b128 v[210:213], v153
	ds_read_b128 v[214:217], v153 offset:2048
	ds_read_b128 v[218:221], v154
	ds_read_b128 v[222:225], v154 offset:2048
	ds_read_b128 v[226:229], v153 offset:4096
	ds_read_b128 v[230:233], v153 offset:6144
	ds_read_b128 v[234:237], v154 offset:4096
	ds_read_b128 v[238:241], v154 offset:6144
	global_load_lds_dwordx4 v[242:243], off
	v_lshl_add_u64 v[242:243], v[140:141], 0, s[86:87]
	s_add_i32 m0, s34, 0xa000
	s_mov_b64 s[86:87], 0x60080
	global_load_lds_dwordx4 v[242:243], off
	v_lshl_add_u64 v[242:243], v[140:141], 0, s[24:25]
	s_add_i32 m0, s34, 0xc000
	v_lshl_add_u64 v[140:141], v[140:141], 0, s[86:87]
	global_load_lds_dwordx4 v[242:243], off
	s_add_i32 m0, s34, 0xe000
	s_nop 0
	global_load_lds_dwordx4 v[140:141], off
	s_waitcnt vmcnt(8)
	s_waitcnt lgkmcnt(0)
	s_barrier
	v_mfma_f32_16x16x32_bf16 v[128:131], v[168:171], v[210:213], v[128:131]
	v_mfma_f32_16x16x32_bf16 v[128:131], v[174:177], v[218:221], v[128:131]
	v_mfma_f32_16x16x32_bf16 v[112:115], v[174:177], v[222:225], v[112:115]
	v_mfma_f32_16x16x32_bf16 v[112:115], v[168:171], v[214:217], v[112:115]
	v_mfma_f32_16x16x32_bf16 v[96:99], v[168:171], v[226:229], v[96:99]
	v_mfma_f32_16x16x32_bf16 v[96:99], v[174:177], v[234:237], v[96:99]
	v_mfma_f32_16x16x32_bf16 v[80:83], v[174:177], v[238:241], v[80:83]
	v_mfma_f32_16x16x32_bf16 v[80:83], v[168:171], v[230:233], v[80:83]
	v_mfma_f32_16x16x32_bf16 v[76:79], v[178:181], v[230:233], v[76:79]
	v_mfma_f32_16x16x32_bf16 v[76:79], v[182:185], v[238:241], v[76:79]
	v_mfma_f32_16x16x32_bf16 v[92:95], v[182:185], v[234:237], v[92:95]
	v_mfma_f32_16x16x32_bf16 v[92:95], v[178:181], v[226:229], v[92:95]
	v_mfma_f32_16x16x32_bf16 v[108:111], v[178:181], v[214:217], v[108:111]
	v_mfma_f32_16x16x32_bf16 v[108:111], v[182:185], v[222:225], v[108:111]
	v_mfma_f32_16x16x32_bf16 v[124:127], v[182:185], v[218:221], v[124:127]
	v_mfma_f32_16x16x32_bf16 v[124:127], v[178:181], v[210:213], v[124:127]
	v_mfma_f32_16x16x32_bf16 v[120:123], v[194:197], v[210:213], v[120:123]
	v_mfma_f32_16x16x32_bf16 v[120:123], v[198:201], v[218:221], v[120:123]
	v_mfma_f32_16x16x32_bf16 v[104:107], v[198:201], v[222:225], v[104:107]
	v_mfma_f32_16x16x32_bf16 v[104:107], v[194:197], v[214:217], v[104:107]
	v_mfma_f32_16x16x32_bf16 v[88:91], v[194:197], v[226:229], v[88:91]
	v_mfma_f32_16x16x32_bf16 v[88:91], v[198:201], v[234:237], v[88:91]
	v_mfma_f32_16x16x32_bf16 v[72:75], v[198:201], v[238:241], v[72:75]
	v_mfma_f32_16x16x32_bf16 v[72:75], v[194:197], v[230:233], v[72:75]
	v_mfma_f32_16x16x32_bf16 v[68:71], v[202:205], v[230:233], v[68:71]
	v_mfma_f32_16x16x32_bf16 v[68:71], v[206:209], v[238:241], v[68:71]
	v_mfma_f32_16x16x32_bf16 v[84:87], v[206:209], v[234:237], v[84:87]
	v_mfma_f32_16x16x32_bf16 v[84:87], v[202:205], v[226:229], v[84:87]
	v_mfma_f32_16x16x32_bf16 v[100:103], v[202:205], v[214:217], v[100:103]
	v_mfma_f32_16x16x32_bf16 v[100:103], v[206:209], v[222:225], v[100:103]
	v_mfma_f32_16x16x32_bf16 v[116:119], v[206:209], v[218:221], v[116:119]
	v_mfma_f32_16x16x32_bf16 v[116:119], v[202:205], v[210:213], v[116:119]
	s_barrier
	v_lshl_add_u64 v[140:141], s[84:85], 0, v[158:159]
	s_add_i32 s84, s67, s3
	s_mov_b32 m0, s84
	ds_read_b128 v[210:213], v153 offset:16384
	ds_read_b128 v[214:217], v153 offset:18432
	ds_read_b128 v[218:221], v154 offset:16384
	ds_read_b128 v[222:225], v154 offset:18432
	ds_read_b128 v[226:229], v153 offset:20480
	ds_read_b128 v[230:233], v153 offset:22528
	ds_read_b128 v[234:237], v154 offset:20480
	ds_read_b128 v[238:241], v154 offset:22528
	global_load_lds_dwordx4 v[140:141], off
	v_lshl_add_u64 v[242:243], v[140:141], 0, s[0:1]
	s_add_i32 m0, s84, 0x2000
	s_add_i32 s84, s72, s3
	global_load_lds_dwordx4 v[242:243], off
	v_lshl_add_u64 v[242:243], v[140:141], 0, s[12:13]
	s_mov_b32 m0, s84
	s_nop 0
	global_load_lds_dwordx4 v[242:243], off
	v_lshl_add_u64 v[242:243], v[140:141], 0, s[14:15]
	s_add_i32 m0, s84, 0x2000
	s_nop 0
	global_load_lds_dwordx4 v[242:243], off
	s_waitcnt vmcnt(4)
	s_waitcnt lgkmcnt(0)
	s_barrier
	v_mfma_f32_16x16x32_bf16 v[64:67], v[168:171], v[210:213], v[64:67]
	v_mfma_f32_16x16x32_bf16 v[64:67], v[174:177], v[218:221], v[64:67]
	v_mfma_f32_16x16x32_bf16 v[48:51], v[174:177], v[222:225], v[48:51]
	v_mfma_f32_16x16x32_bf16 v[48:51], v[168:171], v[214:217], v[48:51]
	v_mfma_f32_16x16x32_bf16 v[32:35], v[168:171], v[226:229], v[32:35]
	v_mfma_f32_16x16x32_bf16 v[32:35], v[174:177], v[234:237], v[32:35]
	v_mfma_f32_16x16x32_bf16 v[16:19], v[174:177], v[238:241], v[16:19]
	v_mfma_f32_16x16x32_bf16 v[16:19], v[168:171], v[230:233], v[16:19]
	v_mfma_f32_16x16x32_bf16 v[12:15], v[178:181], v[230:233], v[12:15]
	v_mfma_f32_16x16x32_bf16 v[12:15], v[182:185], v[238:241], v[12:15]
	v_mfma_f32_16x16x32_bf16 v[28:31], v[182:185], v[234:237], v[28:31]
	v_mfma_f32_16x16x32_bf16 v[28:31], v[178:181], v[226:229], v[28:31]
	v_mfma_f32_16x16x32_bf16 v[44:47], v[178:181], v[214:217], v[44:47]
	v_mfma_f32_16x16x32_bf16 v[44:47], v[182:185], v[222:225], v[44:47]
	v_mfma_f32_16x16x32_bf16 v[60:63], v[182:185], v[218:221], v[60:63]
	v_mfma_f32_16x16x32_bf16 v[60:63], v[178:181], v[210:213], v[60:63]
	v_mfma_f32_16x16x32_bf16 v[56:59], v[194:197], v[210:213], v[56:59]
	v_mfma_f32_16x16x32_bf16 v[56:59], v[198:201], v[218:221], v[56:59]
	v_mfma_f32_16x16x32_bf16 v[40:43], v[198:201], v[222:225], v[40:43]
	v_mfma_f32_16x16x32_bf16 v[40:43], v[194:197], v[214:217], v[40:43]
	v_mfma_f32_16x16x32_bf16 v[24:27], v[194:197], v[226:229], v[24:27]
	v_mfma_f32_16x16x32_bf16 v[24:27], v[198:201], v[234:237], v[24:27]
	v_mfma_f32_16x16x32_bf16 v[8:11], v[198:201], v[238:241], v[8:11]
	v_mfma_f32_16x16x32_bf16 v[8:11], v[194:197], v[230:233], v[8:11]
	v_mfma_f32_16x16x32_bf16 v[4:7], v[202:205], v[230:233], v[4:7]
	v_mfma_f32_16x16x32_bf16 v[4:7], v[206:209], v[238:241], v[4:7]
	v_mfma_f32_16x16x32_bf16 v[20:23], v[206:209], v[234:237], v[20:23]
	v_mfma_f32_16x16x32_bf16 v[20:23], v[202:205], v[226:229], v[20:23]
	v_mfma_f32_16x16x32_bf16 v[36:39], v[202:205], v[214:217], v[36:39]
	v_mfma_f32_16x16x32_bf16 v[36:39], v[206:209], v[222:225], v[36:39]
	v_mfma_f32_16x16x32_bf16 v[52:55], v[206:209], v[218:221], v[52:55]
	v_mfma_f32_16x16x32_bf16 v[52:55], v[202:205], v[210:213], v[52:55]
	s_barrier
	ds_read_b128 v[168:171], v163
	ds_read_b128 v[174:177], v164
	ds_read_b128 v[178:181], v155
	ds_read_b128 v[182:185], v160
	ds_read_b128 v[194:197], v165
	ds_read_b128 v[198:201], v166
	ds_read_b128 v[202:205], v161
	ds_read_b128 v[206:209], v162
	s_mov_b32 m0, s34
	v_lshl_add_u64 v[242:243], s[70:71], 0, v[0:1]
	ds_read_b128 v[210:213], v153 offset:32768
	ds_read_b128 v[214:217], v153 offset:34816
	ds_read_b128 v[218:221], v154 offset:32768
	ds_read_b128 v[222:225], v154 offset:34816
	ds_read_b128 v[226:229], v153 offset:36864
	ds_read_b128 v[230:233], v153 offset:38912
	ds_read_b128 v[234:237], v154 offset:36864
	ds_read_b128 v[238:241], v154 offset:38912
	global_load_lds_dwordx4 v[242:243], off
	v_lshl_add_u64 v[244:245], v[242:243], 0, s[16:17]
	s_mov_b32 m0, s35
	s_nop 0
	global_load_lds_dwordx4 v[244:245], off
	v_lshl_add_u64 v[244:245], v[242:243], 0, s[0:1]
	s_mov_b32 m0, s38
	v_lshl_add_u64 v[242:243], v[242:243], 0, s[18:19]
	global_load_lds_dwordx4 v[244:245], off
	s_mov_b32 m0, s39
	s_nop 0
	global_load_lds_dwordx4 v[242:243], off
	s_waitcnt vmcnt(8)
	s_waitcnt lgkmcnt(0)
	s_barrier
	v_mfma_f32_16x16x32_bf16 v[128:131], v[168:171], v[210:213], v[128:131]
	v_mfma_f32_16x16x32_bf16 v[128:131], v[174:177], v[218:221], v[128:131]
	v_mfma_f32_16x16x32_bf16 v[112:115], v[174:177], v[222:225], v[112:115]
	v_mfma_f32_16x16x32_bf16 v[112:115], v[168:171], v[214:217], v[112:115]
	v_mfma_f32_16x16x32_bf16 v[96:99], v[168:171], v[226:229], v[96:99]
	v_mfma_f32_16x16x32_bf16 v[96:99], v[174:177], v[234:237], v[96:99]
	v_mfma_f32_16x16x32_bf16 v[80:83], v[174:177], v[238:241], v[80:83]
	v_mfma_f32_16x16x32_bf16 v[80:83], v[168:171], v[230:233], v[80:83]
	v_mfma_f32_16x16x32_bf16 v[76:79], v[178:181], v[230:233], v[76:79]
	v_mfma_f32_16x16x32_bf16 v[76:79], v[182:185], v[238:241], v[76:79]
	v_mfma_f32_16x16x32_bf16 v[92:95], v[182:185], v[234:237], v[92:95]
	v_mfma_f32_16x16x32_bf16 v[92:95], v[178:181], v[226:229], v[92:95]
	v_mfma_f32_16x16x32_bf16 v[108:111], v[178:181], v[214:217], v[108:111]
	v_mfma_f32_16x16x32_bf16 v[108:111], v[182:185], v[222:225], v[108:111]
	v_mfma_f32_16x16x32_bf16 v[124:127], v[182:185], v[218:221], v[124:127]
	v_mfma_f32_16x16x32_bf16 v[124:127], v[178:181], v[210:213], v[124:127]
	v_mfma_f32_16x16x32_bf16 v[120:123], v[194:197], v[210:213], v[120:123]
	v_mfma_f32_16x16x32_bf16 v[120:123], v[198:201], v[218:221], v[120:123]
	v_mfma_f32_16x16x32_bf16 v[104:107], v[198:201], v[222:225], v[104:107]
	v_mfma_f32_16x16x32_bf16 v[104:107], v[194:197], v[214:217], v[104:107]
	v_mfma_f32_16x16x32_bf16 v[88:91], v[194:197], v[226:229], v[88:91]
	v_mfma_f32_16x16x32_bf16 v[88:91], v[198:201], v[234:237], v[88:91]
	v_mfma_f32_16x16x32_bf16 v[72:75], v[198:201], v[238:241], v[72:75]
	v_mfma_f32_16x16x32_bf16 v[72:75], v[194:197], v[230:233], v[72:75]
	v_mfma_f32_16x16x32_bf16 v[68:71], v[202:205], v[230:233], v[68:71]
	v_mfma_f32_16x16x32_bf16 v[68:71], v[206:209], v[238:241], v[68:71]
	v_mfma_f32_16x16x32_bf16 v[84:87], v[206:209], v[234:237], v[84:87]
	v_mfma_f32_16x16x32_bf16 v[84:87], v[202:205], v[226:229], v[84:87]
	v_mfma_f32_16x16x32_bf16 v[100:103], v[202:205], v[214:217], v[100:103]
	v_mfma_f32_16x16x32_bf16 v[100:103], v[206:209], v[222:225], v[100:103]
	v_mfma_f32_16x16x32_bf16 v[116:119], v[206:209], v[218:221], v[116:119]
	v_mfma_f32_16x16x32_bf16 v[116:119], v[202:205], v[210:213], v[116:119]
	s_barrier
	s_add_i32 s70, s73, s3
	v_lshl_add_u64 v[242:243], v[140:141], 0, s[22:23]
	s_mov_b32 m0, s70
	ds_read_b128 v[210:213], v153 offset:49152
	ds_read_b128 v[214:217], v153 offset:51200
	ds_read_b128 v[218:221], v154 offset:49152
	ds_read_b128 v[222:225], v154 offset:51200
	ds_read_b128 v[226:229], v153 offset:53248
	ds_read_b128 v[230:233], v153 offset:55296
	ds_read_b128 v[234:237], v154 offset:53248
	ds_read_b128 v[238:241], v154 offset:55296
	global_load_lds_dwordx4 v[242:243], off
	v_lshl_add_u64 v[242:243], v[140:141], 0, s[24:25]
	s_add_i32 m0, s70, 0x2000
	s_add_i32 s70, s77, s3
	global_load_lds_dwordx4 v[242:243], off
	v_lshl_add_u64 v[242:243], v[140:141], 0, s[28:29]
	s_mov_b32 m0, s70
	v_lshl_add_u64 v[140:141], v[140:141], 0, s[36:37]
	global_load_lds_dwordx4 v[242:243], off
	s_add_i32 m0, s70, 0x2000
	s_nop 0
	global_load_lds_dwordx4 v[140:141], off
	s_waitcnt vmcnt(4)
	s_waitcnt lgkmcnt(0)
	s_barrier
	v_mfma_f32_16x16x32_bf16 v[64:67], v[168:171], v[210:213], v[64:67]
	v_mfma_f32_16x16x32_bf16 v[64:67], v[174:177], v[218:221], v[64:67]
	v_mfma_f32_16x16x32_bf16 v[48:51], v[174:177], v[222:225], v[48:51]
	v_mfma_f32_16x16x32_bf16 v[48:51], v[168:171], v[214:217], v[48:51]
	v_mfma_f32_16x16x32_bf16 v[32:35], v[168:171], v[226:229], v[32:35]
	v_mfma_f32_16x16x32_bf16 v[32:35], v[174:177], v[234:237], v[32:35]
	v_mfma_f32_16x16x32_bf16 v[16:19], v[174:177], v[238:241], v[16:19]
	v_mfma_f32_16x16x32_bf16 v[16:19], v[168:171], v[230:233], v[16:19]
	v_mfma_f32_16x16x32_bf16 v[12:15], v[178:181], v[230:233], v[12:15]
	v_mfma_f32_16x16x32_bf16 v[12:15], v[182:185], v[238:241], v[12:15]
	v_mfma_f32_16x16x32_bf16 v[28:31], v[182:185], v[234:237], v[28:31]
	v_mfma_f32_16x16x32_bf16 v[28:31], v[178:181], v[226:229], v[28:31]
	v_mfma_f32_16x16x32_bf16 v[44:47], v[178:181], v[214:217], v[44:47]
	v_mfma_f32_16x16x32_bf16 v[44:47], v[182:185], v[222:225], v[44:47]
	v_mfma_f32_16x16x32_bf16 v[60:63], v[182:185], v[218:221], v[60:63]
	v_mfma_f32_16x16x32_bf16 v[60:63], v[178:181], v[210:213], v[60:63]
	v_mfma_f32_16x16x32_bf16 v[56:59], v[194:197], v[210:213], v[56:59]
	v_mfma_f32_16x16x32_bf16 v[56:59], v[198:201], v[218:221], v[56:59]
	v_mfma_f32_16x16x32_bf16 v[40:43], v[198:201], v[222:225], v[40:43]
	v_mfma_f32_16x16x32_bf16 v[40:43], v[194:197], v[214:217], v[40:43]
	v_mfma_f32_16x16x32_bf16 v[24:27], v[194:197], v[226:229], v[24:27]
	v_mfma_f32_16x16x32_bf16 v[24:27], v[198:201], v[234:237], v[24:27]
	v_mfma_f32_16x16x32_bf16 v[8:11], v[198:201], v[238:241], v[8:11]
	v_mfma_f32_16x16x32_bf16 v[8:11], v[194:197], v[230:233], v[8:11]
	v_mfma_f32_16x16x32_bf16 v[4:7], v[202:205], v[230:233], v[4:7]
	v_mfma_f32_16x16x32_bf16 v[4:7], v[206:209], v[238:241], v[4:7]
	v_mfma_f32_16x16x32_bf16 v[20:23], v[206:209], v[234:237], v[20:23]
	v_mfma_f32_16x16x32_bf16 v[20:23], v[202:205], v[226:229], v[20:23]
	v_mfma_f32_16x16x32_bf16 v[36:39], v[202:205], v[214:217], v[36:39]
	v_mfma_f32_16x16x32_bf16 v[36:39], v[206:209], v[222:225], v[36:39]
	v_mfma_f32_16x16x32_bf16 v[52:55], v[206:209], v[218:221], v[52:55]
	v_mfma_f32_16x16x32_bf16 v[52:55], v[202:205], v[210:213], v[52:55]
	s_barrier
	s_add_i32 s83, s83, 2
	s_add_u32 s68, s68, 0x100
	s_addc_u32 s69, s69, 0
	s_cmp_gt_u32 s83, 13
	s_cbranch_scc0 .LBB0_1135
	s_and_b64 vcc, exec, s[40:41]
	s_cbranch_vccz .Lp5_wr1_epi
	s_barrier
	s_branch .LBB0_1138
